# baseline (speedup 1.0000x reference)
; #define DECODE(Lx, PM, PN) do { int wgid = (Lx); \
;     { int q = nwg / NXCD, r = nwg % NXCD, xcd = wgid % NXCD, off = wgid / NXCD; wgid = (xcd < r ? xcd * (q + 1) : r * (q + 1) + (xcd - r) * q) + off; } \
;     const int nig = WGM * nN, gid = wgid / nig, fm = gid * WGM, gsz = min(nM - fm, WGM); \
;     PM = fm + ((wgid % nig) % gsz); PN = (wgid % nig) / gsz; } while (0)
; template <int MODE>
; DEV void gemm_phase(const bf16_t* __restrict__ A, const bf16_t* __restrict__ Bt, int M, int N, int K, bf16_t* __restrict__ Out, int ldo,
;                     const float* __restrict__ rstd, const float* __restrict__ rope) {
;     ...
;     const bool has_next = (L + (int)gridDim.x) < nwg;
;     int npm = pm, npn = pn; if (has_next) DECODE(L + (int)gridDim.x, npm, npn);
;     const char* nA = (const char*)A + (size_t)npm * tstep; const char* nB = (const char*)Bt + (size_t)npn * tstep;
;     const int brow = pm * BM, bcol = pn * BM;
;     ...
; #pragma unroll
;     for (int a = 0; a < 2; ++a)
; #pragma unroll
;       for (int b = 0; b < 2; ++b)
; #pragma unroll
;         for (int m = 0; m < 4; ++m)
; #pragma unroll
;           for (int n = 0; n < 2; ++n) acc[a][b][m][n] = (f32x4){0.f, 0.f, 0.f, 0.f};
;     pm = npm; pn = npn; cA = nA; cB = nB; L += (int)gridDim.x;
.LBB0_127:
	s_ashr_i32 s19, s18, 31
	s_lshl_b64 s[22:23], s[18:19], 20
	s_add_u32 s19, s66, s22
	s_addc_u32 s42, s67, s23
	s_ashr_i32 s21, s20, 31
	s_lshl_b64 s[24:25], s[20:21], 20
	s_add_u32 s21, s58, s24
	s_addc_u32 s43, s59, s25
	s_add_u32 s44, s58, s26
	s_addc_u32 s45, s59, s27
	v_readlane_b32 s28, v254, 63
	s_add_u32 s46, s28, s8
	v_readlane_b32 s8, v255, 0
	v_mov_b32_e32 v0, 0
	s_addc_u32 s47, s8, s9
	s_mov_b32 s48, -2
	s_mov_b64 s[8:9], 0
	v_mov_b32_e32 v1, v0
	v_mov_b64_e32 v[2:3], 0
	v_mov_b64_e32 v[4:5], 0
	v_mov_b64_e32 v[6:7], 0
	v_mov_b64_e32 v[16:17], 0
	v_mov_b64_e32 v[18:19], 0
	v_mov_b64_e32 v[20:21], 0
	v_mov_b64_e32 v[22:23], 0
	v_mov_b32_e32 v32, v0
	s_waitcnt lgkmcnt(0)
	v_mov_b32_e32 v33, v0
	v_mov_b64_e32 v[34:35], 0
	v_mov_b64_e32 v[36:37], 0
	v_mov_b64_e32 v[38:39], 0
	v_mov_b64_e32 v[48:49], 0
	v_mov_b64_e32 v[50:51], 0
	v_mov_b64_e32 v[52:53], 0
	v_mov_b64_e32 v[54:55], 0
	v_mov_b64_e32 v[8:9], 0
	v_mov_b64_e32 v[10:11], 0
	v_mov_b64_e32 v[12:13], 0
	v_mov_b64_e32 v[14:15], 0
	v_mov_b64_e32 v[24:25], 0
	v_mov_b64_e32 v[26:27], 0
	v_mov_b64_e32 v[28:29], 0
	v_mov_b64_e32 v[30:31], 0
	v_mov_b64_e32 v[40:41], 0
	v_mov_b64_e32 v[42:43], 0
	v_mov_b64_e32 v[44:45], 0
	v_mov_b64_e32 v[46:47], 0
	v_mov_b64_e32 v[56:57], 0
	v_mov_b64_e32 v[58:59], 0
	v_mov_b64_e32 v[60:61], 0
	v_mov_b64_e32 v[62:63], 0
	v_mov_b64_e32 v[64:65], 0
	v_mov_b64_e32 v[66:67], 0
	v_mov_b64_e32 v[68:69], 0
	v_mov_b64_e32 v[70:71], 0
	v_mov_b64_e32 v[80:81], 0
	v_mov_b64_e32 v[82:83], 0
	v_mov_b64_e32 v[84:85], 0
	v_mov_b64_e32 v[86:87], 0
	v_mov_b64_e32 v[96:97], 0
	v_mov_b64_e32 v[98:99], 0
	v_mov_b64_e32 v[100:101], 0
	v_mov_b64_e32 v[102:103], 0
	v_mov_b64_e32 v[112:113], 0
	v_mov_b64_e32 v[114:115], 0
	v_mov_b64_e32 v[116:117], 0
	v_mov_b64_e32 v[118:119], 0
	v_mov_b64_e32 v[72:73], 0
	v_mov_b64_e32 v[74:75], 0
	v_mov_b64_e32 v[76:77], 0
	v_mov_b64_e32 v[78:79], 0
	v_mov_b64_e32 v[88:89], 0
	v_mov_b64_e32 v[90:91], 0
	v_mov_b64_e32 v[92:93], 0
	v_mov_b64_e32 v[94:95], 0
	v_mov_b64_e32 v[104:105], 0
	v_mov_b64_e32 v[106:107], 0
	v_mov_b64_e32 v[108:109], 0
	v_mov_b64_e32 v[110:111], 0
	v_mov_b64_e32 v[120:121], 0
	v_mov_b64_e32 v[122:123], 0
	v_mov_b64_e32 v[124:125], 0
	v_mov_b64_e32 v[126:127], 0
	v_lshl_add_u64 v[128:129], v[160:161], 0, s[26:27]
	v_lshl_add_u64 v[130:131], v[162:163], 0, s[26:27]
	s_mov_b64 s[88:89], 0x80
	v_lshl_add_u32 v248, s41, 8, v170
	v_ashrrev_i32_e32 v249, 31, v248
	v_lshl_add_u64 v[248:249], v[248:249], 2, s[68:69]
	global_load_dword v232, v[248:249], off
	global_load_dword v234, v[248:249], off offset:64
	global_load_dword v236, v[248:249], off offset:128
	global_load_dword v238, v[248:249], off offset:192
	global_load_dword v240, v[248:249], off offset:512
	global_load_dword v242, v[248:249], off offset:576
	global_load_dword v244, v[248:249], off offset:640
	global_load_dword v246, v[248:249], off offset:704
	.p2align 6

; #define DECODE(Lx, PM, PN) do { int wgid = (Lx); \
;     { int q = nwg / NXCD, r = nwg % NXCD, xcd = wgid % NXCD, off = wgid / NXCD; wgid = (xcd < r ? xcd * (q + 1) : r * (q + 1) + (xcd - r) * q) + off; } \
;     const int nig = WGM * nN, gid = wgid / nig, fm = gid * WGM, gsz = min(nM - fm, WGM); \
;     PM = fm + ((wgid % nig) % gsz); PN = (wgid % nig) / gsz; } while (0)
; template <int MODE>
; DEV void gemm_phase(const bf16_t* __restrict__ A, const bf16_t* __restrict__ Bt, int M, int N, int K, bf16_t* __restrict__ Out, int ldo,
;                     const float* __restrict__ rstd, const float* __restrict__ rope) {
;     ...
;     const bool has_next = (L + (int)gridDim.x) < nwg;
;     int npm = pm, npn = pn; if (has_next) DECODE(L + (int)gridDim.x, npm, npn);
;     const char* nA = (const char*)A + (size_t)npm * tstep; const char* nB = (const char*)Bt + (size_t)npn * tstep;
;     const int brow = pm * BM, bcol = pn * BM;
;     ...
; #pragma unroll
;     for (int a = 0; a < 2; ++a)
; #pragma unroll
;       for (int b = 0; b < 2; ++b)
; #pragma unroll
;         for (int m = 0; m < 4; ++m)
; #pragma unroll
;           for (int n = 0; n < 2; ++n) acc[a][b][m][n] = (f32x4){0.f, 0.f, 0.f, 0.f};
;     pm = npm; pn = npn; cA = nA; cB = nB; L += (int)gridDim.x;
.LBB0_492:
	s_ashr_i32 s11, s10, 31
	s_lshl_b64 s[14:15], s[10:11], 20
	s_add_u32 s14, s56, s14
	s_addc_u32 s15, s57, s15
	s_ashr_i32 s13, s12, 31
	s_lshl_b64 s[16:17], s[12:13], 20
	s_add_u32 s11, s74, s16
	s_addc_u32 s13, s75, s17
	s_add_u32 s18, s18, 0x80080
	s_addc_u32 s19, s19, 0
	v_readlane_b32 s22, v255, 1
	s_add_u32 s36, s22, s20
	v_readlane_b32 s20, v255, 2
	v_mov_b32_e32 v0, 0
	s_addc_u32 s37, s20, s21
	s_mov_b32 s38, -2
	v_mov_b32_e32 v1, v0
	v_mov_b64_e32 v[2:3], 0
	v_mov_b64_e32 v[4:5], 0
	v_mov_b64_e32 v[6:7], 0
	v_mov_b64_e32 v[8:9], 0
	v_mov_b64_e32 v[10:11], 0
	v_mov_b64_e32 v[12:13], 0
	v_mov_b64_e32 v[14:15], 0
	v_mov_b64_e32 v[24:25], 0
	v_mov_b64_e32 v[26:27], 0
	v_mov_b64_e32 v[28:29], 0
	v_mov_b64_e32 v[30:31], 0
	v_mov_b64_e32 v[40:41], 0
	v_mov_b64_e32 v[42:43], 0
	v_mov_b64_e32 v[44:45], 0
	v_mov_b64_e32 v[46:47], 0
	v_mov_b64_e32 v[16:17], 0
	v_mov_b64_e32 v[18:19], 0
	v_mov_b64_e32 v[20:21], 0
	v_mov_b64_e32 v[22:23], 0
	v_mov_b64_e32 v[32:33], 0
	v_mov_b64_e32 v[34:35], 0
	v_mov_b64_e32 v[36:37], 0
	v_mov_b64_e32 v[38:39], 0
	v_mov_b64_e32 v[48:49], 0
	v_mov_b64_e32 v[50:51], 0
	v_mov_b64_e32 v[52:53], 0
	v_mov_b64_e32 v[54:55], 0
	v_mov_b64_e32 v[56:57], 0
	v_mov_b64_e32 v[58:59], 0
	v_mov_b64_e32 v[60:61], 0
	v_mov_b64_e32 v[62:63], 0
	v_mov_b64_e32 v[64:65], 0
	v_mov_b64_e32 v[66:67], 0
	v_mov_b64_e32 v[68:69], 0
	v_mov_b64_e32 v[70:71], 0
	v_mov_b64_e32 v[72:73], 0
	v_mov_b64_e32 v[74:75], 0
	v_mov_b64_e32 v[76:77], 0
	v_mov_b64_e32 v[78:79], 0
	v_mov_b64_e32 v[88:89], 0
	v_mov_b64_e32 v[90:91], 0
	v_mov_b64_e32 v[92:93], 0
	v_mov_b64_e32 v[94:95], 0
	v_mov_b64_e32 v[104:105], 0
	v_mov_b64_e32 v[106:107], 0
	v_mov_b64_e32 v[108:109], 0
	v_mov_b64_e32 v[110:111], 0
	v_mov_b64_e32 v[80:81], 0
	v_mov_b64_e32 v[82:83], 0
	v_mov_b64_e32 v[84:85], 0
	v_mov_b64_e32 v[86:87], 0
	v_mov_b64_e32 v[96:97], 0
	v_mov_b64_e32 v[98:99], 0
	v_mov_b64_e32 v[100:101], 0
	v_mov_b64_e32 v[102:103], 0
	v_mov_b64_e32 v[112:113], 0
	v_mov_b64_e32 v[114:115], 0
	v_mov_b64_e32 v[116:117], 0
	v_mov_b64_e32 v[118:119], 0
	v_mov_b64_e32 v[120:121], 0
	v_mov_b64_e32 v[122:123], 0
	v_mov_b64_e32 v[124:125], 0
	v_mov_b64_e32 v[126:127], 0
	s_mov_b64 s[44:45], 0x80
	.p2align 6

; template <int MODE>
; DEV void gemm_phase(const bf16_t* __restrict__ A, const bf16_t* __restrict__ Bt, int M, int N, int K, bf16_t* __restrict__ Out, int ldo,
;                     const float* __restrict__ rstd, const float* __restrict__ rope) {
;     ...
; #pragma unroll
;       for (int ai = 0; ai < 2; ++ai)
; #pragma unroll
;         for (int m = 0; m < 4; ++m) {
;           const int row = brow + ai * HALF + wr * 64 + m * 16 + fr; const float rs = rstd[row];
;     ...
; #pragma unroll
;     for (int a = 0; a < 2; ++a)
; #pragma unroll
;       for (int b = 0; b < 2; ++b)
; #pragma unroll
;         for (int m = 0; m < 4; ++m)
; #pragma unroll
;           for (int n = 0; n < 2; ++n) acc[a][b][m][n] = (f32x4){0.f, 0.f, 0.f, 0.f};
;     pm = npm; pn = npn; cA = nA; cB = nB; L += (int)gridDim.x;
.LBB0_617:
	s_ashr_i32 s9, s8, 31
	s_lshl_b64 s[14:15], s[8:9], 20
	s_add_u32 s9, s66, s14
	s_addc_u32 s36, s67, s15
	s_ashr_i32 s11, s10, 31
	s_lshl_b64 s[16:17], s[10:11], 20
	s_add_u32 s11, s78, s16
	s_addc_u32 s37, s79, s17
	s_add_u32 s38, s58, s20
	s_addc_u32 s39, s59, s21
	v_lshl_add_u64 v[140:141], v[136:137], 0, s[20:21]
	v_lshl_add_u64 v[142:143], v[138:139], 0, s[20:21]
	v_readlane_b32 s20, v255, 3
	s_add_u32 s40, s20, s18
	v_readlane_b32 s18, v255, 4
	v_mov_b32_e32 v0, 0
	s_addc_u32 s41, s18, s19
	s_mov_b32 s42, -2
	s_mov_b64 s[18:19], 0
	v_mov_b32_e32 v1, v0
	v_mov_b64_e32 v[2:3], 0
	v_mov_b64_e32 v[8:9], 0
	v_mov_b64_e32 v[10:11], 0
	v_mov_b64_e32 v[16:17], 0
	v_mov_b64_e32 v[18:19], 0
	v_mov_b64_e32 v[20:21], 0
	v_mov_b64_e32 v[22:23], 0
	v_mov_b64_e32 v[32:33], 0
	v_mov_b64_e32 v[34:35], 0
	v_mov_b64_e32 v[36:37], 0
	v_mov_b64_e32 v[38:39], 0
	v_mov_b64_e32 v[48:49], 0
	v_mov_b64_e32 v[50:51], 0
	v_mov_b64_e32 v[52:53], 0
	v_mov_b64_e32 v[54:55], 0
	v_mov_b64_e32 v[4:5], 0
	v_mov_b64_e32 v[6:7], 0
	v_mov_b64_e32 v[12:13], 0
	v_mov_b64_e32 v[14:15], 0
	v_mov_b64_e32 v[24:25], 0
	v_mov_b64_e32 v[26:27], 0
	v_mov_b64_e32 v[28:29], 0
	v_mov_b64_e32 v[30:31], 0
	v_mov_b64_e32 v[40:41], 0
	v_mov_b64_e32 v[42:43], 0
	v_mov_b64_e32 v[44:45], 0
	v_mov_b64_e32 v[46:47], 0
	v_mov_b64_e32 v[56:57], 0
	v_mov_b64_e32 v[58:59], 0
	v_mov_b64_e32 v[60:61], 0
	v_mov_b64_e32 v[62:63], 0
	v_mov_b64_e32 v[64:65], 0
	v_mov_b64_e32 v[66:67], 0
	v_mov_b64_e32 v[68:69], 0
	v_mov_b64_e32 v[70:71], 0
	v_mov_b64_e32 v[80:81], 0
	v_mov_b64_e32 v[82:83], 0
	v_mov_b64_e32 v[84:85], 0
	v_mov_b64_e32 v[86:87], 0
	v_mov_b64_e32 v[96:97], 0
	v_mov_b64_e32 v[98:99], 0
	v_mov_b64_e32 v[100:101], 0
	v_mov_b64_e32 v[102:103], 0
	v_mov_b64_e32 v[112:113], 0
	v_mov_b64_e32 v[114:115], 0
	v_mov_b64_e32 v[116:117], 0
	v_mov_b64_e32 v[118:119], 0
	v_mov_b64_e32 v[72:73], 0
	v_mov_b64_e32 v[74:75], 0
	v_mov_b64_e32 v[76:77], 0
	v_mov_b64_e32 v[78:79], 0
	v_mov_b64_e32 v[88:89], 0
	v_mov_b64_e32 v[90:91], 0
	v_mov_b64_e32 v[92:93], 0
	v_mov_b64_e32 v[94:95], 0
	v_mov_b64_e32 v[104:105], 0
	v_mov_b64_e32 v[106:107], 0
	v_mov_b64_e32 v[108:109], 0
	v_mov_b64_e32 v[110:111], 0
	v_mov_b64_e32 v[120:121], 0
	v_mov_b64_e32 v[122:123], 0
	v_mov_b64_e32 v[124:125], 0
	v_mov_b64_e32 v[126:127], 0
	s_mov_b64 s[46:47], 0x80
	v_lshl_add_u32 v248, s35, 8, v144
	v_ashrrev_i32_e32 v249, 31, v248
	v_lshl_add_u64 v[248:249], v[248:249], 2, s[68:69]
	global_load_dword v232, v[248:249], off
	global_load_dword v234, v[248:249], off offset:64
	global_load_dword v236, v[248:249], off offset:128
	global_load_dword v238, v[248:249], off offset:192
	global_load_dword v240, v[248:249], off offset:512
	global_load_dword v242, v[248:249], off offset:576
	global_load_dword v244, v[248:249], off offset:640
	global_load_dword v246, v[248:249], off offset:704
	.p2align 6

; #define DECODE(Lx, PM, PN) do { int wgid = (Lx); \
;     { int q = nwg / NXCD, r = nwg % NXCD, xcd = wgid % NXCD, off = wgid / NXCD; wgid = (xcd < r ? xcd * (q + 1) : r * (q + 1) + (xcd - r) * q) + off; } \
;     const int nig = WGM * nN, gid = wgid / nig, fm = gid * WGM, gsz = min(nM - fm, WGM); \
;     PM = fm + ((wgid % nig) % gsz); PN = (wgid % nig) / gsz; } while (0)
; template <int MODE>
; DEV void gemm_phase(const bf16_t* __restrict__ A, const bf16_t* __restrict__ Bt, int M, int N, int K, bf16_t* __restrict__ Out, int ldo,
;                     const float* __restrict__ rstd, const float* __restrict__ rope) {
;     ...
;     const bool has_next = (L + (int)gridDim.x) < nwg;
;     int npm = pm, npn = pn; if (has_next) DECODE(L + (int)gridDim.x, npm, npn);
;     const char* nA = (const char*)A + (size_t)npm * tstep; const char* nB = (const char*)Bt + (size_t)npn * tstep;
;     const int brow = pm * BM, bcol = pn * BM;
;     ...
; #pragma unroll
;     for (int a = 0; a < 2; ++a)
; #pragma unroll
;       for (int b = 0; b < 2; ++b)
; #pragma unroll
;         for (int m = 0; m < 4; ++m)
; #pragma unroll
;           for (int n = 0; n < 2; ++n) acc[a][b][m][n] = (f32x4){0.f, 0.f, 0.f, 0.f};
;     pm = npm; pn = npn; cA = nA; cB = nB; L += (int)gridDim.x;
.LBB0_689:
	s_mul_i32 s8, s28, 0x2c0000
	s_mul_hi_i32 s9, s28, 0x2c0000
	s_add_u32 s8, s86, s8
	s_addc_u32 s9, s87, s9
	s_mul_i32 s10, s29, 0x2c0000
	s_mul_hi_i32 s11, s29, 0x2c0000
	s_add_u32 s34, s82, s10
	s_addc_u32 s35, s83, s11
	v_readlane_b32 s16, v255, 5
	s_add_u32 s36, s16, s14
	v_readlane_b32 s14, v255, 6
	v_mov_b32_e32 v0, 0
	s_addc_u32 s37, s14, s15
	s_mov_b32 s38, -2
	v_mov_b32_e32 v1, v0
	v_mov_b64_e32 v[2:3], 0
	v_mov_b64_e32 v[4:5], 0
	v_mov_b64_e32 v[6:7], 0
	v_mov_b64_e32 v[8:9], 0
	v_mov_b64_e32 v[10:11], 0
	v_mov_b64_e32 v[12:13], 0
	v_mov_b64_e32 v[14:15], 0
	v_mov_b64_e32 v[24:25], 0
	v_mov_b64_e32 v[26:27], 0
	v_mov_b64_e32 v[28:29], 0
	v_mov_b64_e32 v[30:31], 0
	v_mov_b64_e32 v[40:41], 0
	v_mov_b64_e32 v[42:43], 0
	v_mov_b64_e32 v[44:45], 0
	v_mov_b64_e32 v[46:47], 0
	v_mov_b64_e32 v[16:17], 0
	v_mov_b64_e32 v[18:19], 0
	v_mov_b64_e32 v[20:21], 0
	v_mov_b64_e32 v[22:23], 0
	v_mov_b64_e32 v[32:33], 0
	v_mov_b64_e32 v[34:35], 0
	v_mov_b64_e32 v[36:37], 0
	v_mov_b64_e32 v[38:39], 0
	v_mov_b64_e32 v[48:49], 0
	v_mov_b64_e32 v[50:51], 0
	v_mov_b64_e32 v[52:53], 0
	v_mov_b64_e32 v[54:55], 0
	v_mov_b64_e32 v[56:57], 0
	v_mov_b64_e32 v[58:59], 0
	v_mov_b64_e32 v[60:61], 0
	v_mov_b64_e32 v[62:63], 0
	v_mov_b64_e32 v[64:65], 0
	v_mov_b64_e32 v[66:67], 0
	v_mov_b64_e32 v[68:69], 0
	v_mov_b64_e32 v[70:71], 0
	v_mov_b64_e32 v[72:73], 0
	v_mov_b64_e32 v[74:75], 0
	v_mov_b64_e32 v[76:77], 0
	v_mov_b64_e32 v[78:79], 0
	v_mov_b64_e32 v[88:89], 0
	v_mov_b64_e32 v[90:91], 0
	v_mov_b64_e32 v[92:93], 0
	v_mov_b64_e32 v[94:95], 0
	v_mov_b64_e32 v[104:105], 0
	v_mov_b64_e32 v[106:107], 0
	v_mov_b64_e32 v[108:109], 0
	v_mov_b64_e32 v[110:111], 0
	v_mov_b64_e32 v[80:81], 0
	v_mov_b64_e32 v[82:83], 0
	v_mov_b64_e32 v[84:85], 0
	v_mov_b64_e32 v[86:87], 0
	v_mov_b64_e32 v[96:97], 0
	v_mov_b64_e32 v[98:99], 0
	v_mov_b64_e32 v[100:101], 0
	v_mov_b64_e32 v[102:103], 0
	v_mov_b64_e32 v[112:113], 0
	v_mov_b64_e32 v[114:115], 0
	v_mov_b64_e32 v[116:117], 0
	v_mov_b64_e32 v[118:119], 0
	v_mov_b64_e32 v[120:121], 0
	v_mov_b64_e32 v[122:123], 0
	v_mov_b64_e32 v[124:125], 0
	v_mov_b64_e32 v[126:127], 0
	s_mov_b64 s[42:43], 0x80
	.p2align 6
